# speedup vs baseline: 1.0025x; 1.0010x over previous
.LBB0_1465:
	s_lshl_b32 s4, s0, 1
	s_and_b32 s6, s4, 0x70000
	s_ashr_i32 s4, s1, 3
	s_ashr_i32 s5, s4, 31
	v_mov_b32_e32 v24, v190
	s_lshl_b64 s[4:5], s[4:5], 20
	v_readlane_b32 s8, v237, 61
	v_readlane_b32 s9, v237, 62
	v_lshrrev_b32_e32 v0, 1, v24
	s_add_u32 s4, s8, s4
	v_and_b32_e32 v25, 15, v24
	v_and_b32_e32 v0, 24, v0
	s_addc_u32 s5, s9, s5
	v_lshlrev_b32_e32 v128, 13, v25
	v_add_u32_e32 v0, s21, v0
	v_mov_b32_e32 v1, v129
	s_add_u32 s4, s4, s6
	v_lshl_add_u64 v[16:17], v[0:1], 2, v[128:129]
	s_addc_u32 s5, s5, 0
	v_lshlrev_b32_e32 v128, 12, v25
	v_lshl_add_u64 v[2:3], s[4:5], 0, v[128:129]
	v_mov_b32_e32 v26, 0
	v_cmp_gt_u32_e64 s[40:41], 8, v25
	v_lshl_add_u64 v[18:19], v[0:1], 1, v[2:3]
	v_lshl_add_u64 v[20:21], s[80:81], 0, v[16:17]
	v_add_co_u32_e32 v20, vcc, 0x100000, v20
	s_nop 1
	v_addc_co_u32_e32 v21, vcc, 0, v21, vcc
	v_lshl_add_u64 v[22:23], s[80:81], 0, v[18:19]
	v_add_co_u32_e32 v8, vcc, 0x6a80000, v22
	s_nop 1
	v_addc_co_u32_e32 v9, vcc, 0, v23, vcc
	v_add_co_u32_e32 v22, vcc, 0x6a00000, v22
	s_nop 1
	v_addc_co_u32_e32 v23, vcc, 0, v23, vcc
	v_mov_b32_e32 v46, 0
	v_mov_b32_e32 v47, 0
	v_mov_b32_e32 v48, 0
	v_mov_b32_e32 v49, 0
	v_mov_b32_e32 v50, 0
	v_mov_b32_e32 v51, 0
	v_mov_b32_e32 v52, 0
	v_mov_b32_e32 v53, 0
	v_mov_b32_e32 v54, 0
	v_mov_b32_e32 v55, 0
	v_mov_b32_e32 v56, 0
	v_mov_b32_e32 v57, 0
	v_mov_b32_e32 v58, 0
	v_mov_b32_e32 v59, 0
	v_mov_b32_e32 v60, 0
	v_mov_b32_e32 v61, 0
	v_mov_b32_e32 v62, 0
	v_mov_b32_e32 v63, 0
	v_mov_b32_e32 v64, 0
	v_mov_b32_e32 v65, 0
	v_mov_b32_e32 v66, 0
	v_mov_b32_e32 v67, 0
	v_mov_b32_e32 v68, 0
	v_mov_b32_e32 v69, 0
	v_mov_b32_e32 v70, 0
	v_mov_b32_e32 v71, 0
	v_mov_b32_e32 v72, 0
	v_mov_b32_e32 v73, 0
	v_mov_b32_e32 v74, 0
	v_mov_b32_e32 v75, 0
	v_mov_b32_e32 v76, 0
	v_mov_b32_e32 v77, 0
	s_and_saveexec_b64 s[4:5], s[40:41]
	global_load_dwordx4 v[46:49], v[20:21], off
	global_load_dwordx4 v[50:53], v[20:21], off offset:16
	global_load_dwordx4 v[54:57], v[20:21], off offset:128
	global_load_dwordx4 v[58:61], v[20:21], off offset:144
	global_load_dwordx4 v[62:65], v[20:21], off offset:256
	global_load_dwordx4 v[66:69], v[20:21], off offset:272
	global_load_dwordx4 v[70:73], v[20:21], off offset:384
	global_load_dwordx4 v[74:77], v[20:21], off offset:400
	s_or_b64 exec, exec, s[4:5]
	global_load_dwordx4 v[78:81], v[22:23], off
	global_load_dwordx4 v[82:85], v[8:9], off
	global_load_dwordx4 v[86:89], v[22:23], off offset:64
	global_load_dwordx4 v[90:93], v[8:9], off offset:64
	global_load_dwordx4 v[94:97], v[22:23], off offset:128
	global_load_dwordx4 v[98:101], v[8:9], off offset:128
	global_load_dwordx4 v[102:105], v[22:23], off offset:192
	global_load_dwordx4 v[106:109], v[8:9], off offset:192
	s_waitcnt vmcnt(0)
	v_mul_f32_e32 v10, v47, v47
	v_fma_f32 v10, v46, v46, v10
	v_mul_f32_e32 v11, v49, v49
	v_fma_f32 v11, v48, v48, v11
	v_add_f32_e32 v12, v10, v11
	v_mul_f32_e32 v13, v51, v51
	v_fma_f32 v13, v50, v50, v13
	v_mul_f32_e32 v14, v53, v53
	v_fma_f32 v14, v52, v52, v14
	v_add_f32_e32 v15, v13, v14
	v_add_f32_e32 v12, v12, v15
	v_add_f32_e32 v26, v26, v12
	v_mul_f32_e32 v10, v55, v55
	v_fma_f32 v10, v54, v54, v10
	v_mul_f32_e32 v11, v57, v57
	v_fma_f32 v11, v56, v56, v11
	v_add_f32_e32 v12, v10, v11
	v_mul_f32_e32 v13, v59, v59
	v_fma_f32 v13, v58, v58, v13
	v_mul_f32_e32 v14, v61, v61
	v_fma_f32 v14, v60, v60, v14
	v_add_f32_e32 v15, v13, v14
	v_add_f32_e32 v12, v12, v15
	v_add_f32_e32 v26, v26, v12
	v_mul_f32_e32 v10, v63, v63
	v_fma_f32 v10, v62, v62, v10
	v_mul_f32_e32 v11, v65, v65
	v_fma_f32 v11, v64, v64, v11
	v_add_f32_e32 v12, v10, v11
	v_mul_f32_e32 v13, v67, v67
	v_fma_f32 v13, v66, v66, v13
	v_mul_f32_e32 v14, v69, v69
	v_fma_f32 v14, v68, v68, v14
	v_add_f32_e32 v15, v13, v14
	v_add_f32_e32 v12, v12, v15
	v_add_f32_e32 v26, v26, v12
	v_mul_f32_e32 v10, v71, v71
	v_fma_f32 v10, v70, v70, v10
	v_mul_f32_e32 v11, v73, v73
	v_fma_f32 v11, v72, v72, v11
	v_add_f32_e32 v12, v10, v11
	v_mul_f32_e32 v13, v75, v75
	v_fma_f32 v13, v74, v74, v13
	v_mul_f32_e32 v14, v77, v77
	v_fma_f32 v14, v76, v76, v14
	v_add_f32_e32 v15, v13, v14
	v_add_f32_e32 v12, v12, v15
	v_add_f32_e32 v26, v26, v12
	v_cvt_pk_bf16_f32 v46, v46, v47
	v_cvt_pk_bf16_f32 v47, v48, v49
	v_cvt_pk_bf16_f32 v48, v50, v51
	v_cvt_pk_bf16_f32 v49, v52, v53
	v_cvt_pk_bf16_f32 v54, v54, v55
	v_cvt_pk_bf16_f32 v55, v56, v57
	v_cvt_pk_bf16_f32 v56, v58, v59
	v_cvt_pk_bf16_f32 v57, v60, v61
	v_cvt_pk_bf16_f32 v62, v62, v63
	v_cvt_pk_bf16_f32 v63, v64, v65
	v_cvt_pk_bf16_f32 v64, v66, v67
	v_cvt_pk_bf16_f32 v65, v68, v69
	v_cvt_pk_bf16_f32 v70, v70, v71
	v_cvt_pk_bf16_f32 v71, v72, v73
	v_cvt_pk_bf16_f32 v72, v74, v75
	v_cvt_pk_bf16_f32 v73, v76, v77
	s_nop 1
	v_mfma_f32_16x16x32_bf16 v[0:3], v[46:49], v[78:81], 0
	v_mfma_f32_16x16x32_bf16 v[4:7], v[46:49], v[82:85], 0
	v_mfma_f32_16x16x32_bf16 v[0:3], v[54:57], v[86:89], v[0:3]
	v_mfma_f32_16x16x32_bf16 v[4:7], v[54:57], v[90:93], v[4:7]
	v_mfma_f32_16x16x32_bf16 v[0:3], v[62:65], v[94:97], v[0:3]
	v_mfma_f32_16x16x32_bf16 v[4:7], v[62:65], v[98:101], v[4:7]
	v_mfma_f32_16x16x32_bf16 v[0:3], v[70:73], v[102:105], v[0:3]
	v_mfma_f32_16x16x32_bf16 v[4:7], v[70:73], v[106:109], v[4:7]
	s_and_saveexec_b64 s[4:5], s[40:41]
	global_load_dwordx4 v[46:49], v[20:21], off offset:512
	global_load_dwordx4 v[50:53], v[20:21], off offset:528
	global_load_dwordx4 v[54:57], v[20:21], off offset:640
	global_load_dwordx4 v[58:61], v[20:21], off offset:656
	global_load_dwordx4 v[62:65], v[20:21], off offset:768
	global_load_dwordx4 v[66:69], v[20:21], off offset:784
	global_load_dwordx4 v[70:73], v[20:21], off offset:896
	global_load_dwordx4 v[74:77], v[20:21], off offset:912
	s_or_b64 exec, exec, s[4:5]
	global_load_dwordx4 v[78:81], v[22:23], off offset:256
	global_load_dwordx4 v[82:85], v[8:9], off offset:256
	global_load_dwordx4 v[86:89], v[22:23], off offset:320
	global_load_dwordx4 v[90:93], v[8:9], off offset:320
	global_load_dwordx4 v[94:97], v[22:23], off offset:384
	global_load_dwordx4 v[98:101], v[8:9], off offset:384
	global_load_dwordx4 v[102:105], v[22:23], off offset:448
	global_load_dwordx4 v[106:109], v[8:9], off offset:448
	s_waitcnt vmcnt(0)
	v_mul_f32_e32 v10, v47, v47
	v_fma_f32 v10, v46, v46, v10
	v_mul_f32_e32 v11, v49, v49
	v_fma_f32 v11, v48, v48, v11
	v_add_f32_e32 v12, v10, v11
	v_mul_f32_e32 v13, v51, v51
	v_fma_f32 v13, v50, v50, v13
	v_mul_f32_e32 v14, v53, v53
	v_fma_f32 v14, v52, v52, v14
	v_add_f32_e32 v15, v13, v14
	v_add_f32_e32 v12, v12, v15
	v_add_f32_e32 v26, v26, v12
	v_mul_f32_e32 v10, v55, v55
	v_fma_f32 v10, v54, v54, v10
	v_mul_f32_e32 v11, v57, v57
	v_fma_f32 v11, v56, v56, v11
	v_add_f32_e32 v12, v10, v11
	v_mul_f32_e32 v13, v59, v59
	v_fma_f32 v13, v58, v58, v13
	v_mul_f32_e32 v14, v61, v61
	v_fma_f32 v14, v60, v60, v14
	v_add_f32_e32 v15, v13, v14
	v_add_f32_e32 v12, v12, v15
	v_add_f32_e32 v26, v26, v12
	v_mul_f32_e32 v10, v63, v63
	v_fma_f32 v10, v62, v62, v10
	v_mul_f32_e32 v11, v65, v65
	v_fma_f32 v11, v64, v64, v11
	v_add_f32_e32 v12, v10, v11
	v_mul_f32_e32 v13, v67, v67
	v_fma_f32 v13, v66, v66, v13
	v_mul_f32_e32 v14, v69, v69
	v_fma_f32 v14, v68, v68, v14
	v_add_f32_e32 v15, v13, v14
	v_add_f32_e32 v12, v12, v15
	v_add_f32_e32 v26, v26, v12
	v_mul_f32_e32 v10, v71, v71
	v_fma_f32 v10, v70, v70, v10
	v_mul_f32_e32 v11, v73, v73
	v_fma_f32 v11, v72, v72, v11
	v_add_f32_e32 v12, v10, v11
	v_mul_f32_e32 v13, v75, v75
	v_fma_f32 v13, v74, v74, v13
	v_mul_f32_e32 v14, v77, v77
	v_fma_f32 v14, v76, v76, v14
	v_add_f32_e32 v15, v13, v14
	v_add_f32_e32 v12, v12, v15
	v_add_f32_e32 v26, v26, v12
	v_cvt_pk_bf16_f32 v46, v46, v47
	v_cvt_pk_bf16_f32 v47, v48, v49
	v_cvt_pk_bf16_f32 v48, v50, v51
	v_cvt_pk_bf16_f32 v49, v52, v53
	v_cvt_pk_bf16_f32 v54, v54, v55
	v_cvt_pk_bf16_f32 v55, v56, v57
	v_cvt_pk_bf16_f32 v56, v58, v59
	v_cvt_pk_bf16_f32 v57, v60, v61
	v_cvt_pk_bf16_f32 v62, v62, v63
	v_cvt_pk_bf16_f32 v63, v64, v65
	v_cvt_pk_bf16_f32 v64, v66, v67
	v_cvt_pk_bf16_f32 v65, v68, v69
	v_cvt_pk_bf16_f32 v70, v70, v71
	v_cvt_pk_bf16_f32 v71, v72, v73
	v_cvt_pk_bf16_f32 v72, v74, v75
	v_cvt_pk_bf16_f32 v73, v76, v77
	s_nop 1
	v_mfma_f32_16x16x32_bf16 v[0:3], v[46:49], v[78:81], v[0:3]
	v_mfma_f32_16x16x32_bf16 v[4:7], v[46:49], v[82:85], v[4:7]
	v_mfma_f32_16x16x32_bf16 v[0:3], v[54:57], v[86:89], v[0:3]
	v_mfma_f32_16x16x32_bf16 v[4:7], v[54:57], v[90:93], v[4:7]
	v_mfma_f32_16x16x32_bf16 v[0:3], v[62:65], v[94:97], v[0:3]
	v_mfma_f32_16x16x32_bf16 v[4:7], v[62:65], v[98:101], v[4:7]
	v_mfma_f32_16x16x32_bf16 v[0:3], v[70:73], v[102:105], v[0:3]
	v_mfma_f32_16x16x32_bf16 v[4:7], v[70:73], v[106:109], v[4:7]
	s_nop 3
